# speedup vs baseline: 1.0635x; 1.0412x over previous
.LBB0_72:
	v_mov_b32_e32 v1, 0
	global_load_dword v2, v1, s[90:91] offset:14
	v_bfe_u32 v217, v0, 10, 10
	v_bfe_u32 v219, v0, 20, 10
	v_or3_b32 v0, v216, v217, v219
	v_cmp_eq_u32_e64 s[88:89], 0, v0
	s_waitcnt vmcnt(0)
	s_barrier
	s_waitcnt vmcnt(0)
	v_readfirstlane_b32 s0, v2
	s_nop 1
	v_writelane_b32 v253, s0, 32
	s_and_saveexec_b64 s[0:1], s[88:89]
	s_cbranch_execz .LBB0_82
	buffer_wbl2 sc1
	s_load_dwordx2 s[4:5], s[90:91], -0x8
	s_load_dword s6, s[90:91], 0x0
	s_and_b32 s7, s2, 7
	s_lshl_b32 s7, s7, 7
	v_mov_b32_e32 v0, s7
	v_mov_b32_e32 v1, 1
	v_mov_b32_e32 v3, 0
	s_waitcnt vmcnt(0) lgkmcnt(0)
	global_atomic_add v2, v0, v1, s[4:5] offset:1024 sc0
	s_lshr_b32 s6, s6, 3
	s_mul_i32 s6, s6, 1
	s_add_i32 s6, s6, -1
	s_waitcnt vmcnt(0)
	v_cmp_eq_u32_e32 vcc, s6, v2
	s_cbranch_vccz .Lgs1_poll
	global_atomic_add v2, v3, v1, s[4:5] offset:512 sc0
	s_movk_i32 s6, 7
	s_waitcnt vmcnt(0)
	v_cmp_eq_u32_e32 vcc, s6, v2
	s_cbranch_vccz .Lgs1_poll
	global_atomic_add v3, v1, s[4:5] offset:2048
	global_atomic_add v3, v1, s[4:5] offset:2176
	global_atomic_add v3, v1, s[4:5] offset:2304
	global_atomic_add v3, v1, s[4:5] offset:2432
	global_atomic_add v3, v1, s[4:5] offset:2560
	global_atomic_add v3, v1, s[4:5] offset:2688
	global_atomic_add v3, v1, s[4:5] offset:2816
	global_atomic_add v3, v1, s[4:5] offset:2944
.Lgs1_poll:
	global_load_dword v2, v0, s[4:5] offset:2048 sc1
	s_waitcnt vmcnt(0)
	v_cmp_le_u32_e32 vcc, 1, v2
	s_cbranch_vccnz .Lgs1_done
	s_sleep 1
	s_branch .Lgs1_poll

.LBB0_90:
	s_or_b64 exec, exec, s[6:7]
	s_waitcnt vmcnt(0)
	s_barrier
	s_and_saveexec_b64 s[4:5], s[88:89]
	s_cbranch_execz .LBB0_100
	buffer_wbl2 sc1
	s_load_dwordx2 s[6:7], s[90:91], -0x8
	s_load_dword s8, s[90:91], 0x0
	s_and_b32 s9, s2, 7
	s_lshl_b32 s9, s9, 7
	v_mov_b32_e32 v0, s9
	v_mov_b32_e32 v1, 1
	v_mov_b32_e32 v3, 0
	s_waitcnt vmcnt(0) lgkmcnt(0)
	global_atomic_add v2, v0, v1, s[6:7] offset:1024 sc0
	s_lshr_b32 s8, s8, 3
	s_mul_i32 s8, s8, 2
	s_add_i32 s8, s8, -1
	s_waitcnt vmcnt(0)
	v_cmp_eq_u32_e32 vcc, s8, v2
	s_cbranch_vccz .Lgs2_poll
	global_atomic_add v2, v3, v1, s[6:7] offset:512 sc0
	s_movk_i32 s8, 15
	s_waitcnt vmcnt(0)
	v_cmp_eq_u32_e32 vcc, s8, v2
	s_cbranch_vccz .Lgs2_poll
	global_atomic_add v3, v1, s[6:7] offset:2048
	global_atomic_add v3, v1, s[6:7] offset:2176
	global_atomic_add v3, v1, s[6:7] offset:2304
	global_atomic_add v3, v1, s[6:7] offset:2432
	global_atomic_add v3, v1, s[6:7] offset:2560
	global_atomic_add v3, v1, s[6:7] offset:2688
	global_atomic_add v3, v1, s[6:7] offset:2816
	global_atomic_add v3, v1, s[6:7] offset:2944
.Lgs2_poll:
	global_load_dword v2, v0, s[6:7] offset:2048 sc1
	s_waitcnt vmcnt(0)
	v_cmp_le_u32_e32 vcc, 2, v2
	s_cbranch_vccnz .Lgs2_done
	s_sleep 1
	s_branch .Lgs2_poll

.LBB0_108:
	s_or_b64 exec, exec, s[0:1]
	s_waitcnt vmcnt(0)
	s_barrier
	s_and_saveexec_b64 s[0:1], s[88:89]
	s_cbranch_execz .LBB0_118
	buffer_wbl2 sc1
	s_load_dwordx2 s[4:5], s[90:91], -0x8
	s_load_dword s6, s[90:91], 0x0
	s_and_b32 s7, s2, 7
	s_lshl_b32 s7, s7, 7
	v_mov_b32_e32 v0, s7
	v_mov_b32_e32 v1, 1
	v_mov_b32_e32 v3, 0
	s_waitcnt vmcnt(0) lgkmcnt(0)
	global_atomic_add v2, v0, v1, s[4:5] offset:1024 sc0
	s_lshr_b32 s6, s6, 3
	s_mul_i32 s6, s6, 3
	s_add_i32 s6, s6, -1
	s_waitcnt vmcnt(0)
	v_cmp_eq_u32_e32 vcc, s6, v2
	s_cbranch_vccz .Lgs3_poll
	global_atomic_add v2, v3, v1, s[4:5] offset:512 sc0
	s_movk_i32 s6, 23
	s_waitcnt vmcnt(0)
	v_cmp_eq_u32_e32 vcc, s6, v2
	s_cbranch_vccz .Lgs3_poll
	global_atomic_add v3, v1, s[4:5] offset:2048
	global_atomic_add v3, v1, s[4:5] offset:2176
	global_atomic_add v3, v1, s[4:5] offset:2304
	global_atomic_add v3, v1, s[4:5] offset:2432
	global_atomic_add v3, v1, s[4:5] offset:2560
	global_atomic_add v3, v1, s[4:5] offset:2688
	global_atomic_add v3, v1, s[4:5] offset:2816
	global_atomic_add v3, v1, s[4:5] offset:2944
.Lgs3_poll:
	global_load_dword v2, v0, s[4:5] offset:2048 sc1
	s_waitcnt vmcnt(0)
	v_cmp_le_u32_e32 vcc, 3, v2
	s_cbranch_vccnz .Lgs3_done
	s_sleep 1
	s_branch .Lgs3_poll

.LBB0_681:
	s_waitcnt vmcnt(63) expcnt(7) lgkmcnt(15)
	s_waitcnt vmcnt(0)
	s_barrier
	s_and_saveexec_b64 s[0:1], s[88:89]
	s_cbranch_execz .LBB0_691
	buffer_wbl2 sc1
	s_load_dwordx2 s[4:5], s[90:91], -0x8
	s_load_dword s6, s[90:91], 0x0
	s_and_b32 s7, s2, 7
	s_lshl_b32 s7, s7, 7
	v_mov_b32_e32 v0, s7
	v_mov_b32_e32 v1, 1
	v_mov_b32_e32 v3, 0
	s_waitcnt vmcnt(0) lgkmcnt(0)
	global_atomic_add v2, v0, v1, s[4:5] offset:1024 sc0
	s_lshr_b32 s6, s6, 3
	s_mul_i32 s6, s6, 4
	s_add_i32 s6, s6, -1
	s_waitcnt vmcnt(0)
	v_cmp_eq_u32_e32 vcc, s6, v2
	s_cbranch_vccz .Lgs4_poll
	global_atomic_add v2, v3, v1, s[4:5] offset:512 sc0
	s_movk_i32 s6, 31
	s_waitcnt vmcnt(0)
	v_cmp_eq_u32_e32 vcc, s6, v2
	s_cbranch_vccz .Lgs4_poll
	global_atomic_add v3, v1, s[4:5] offset:2048
	global_atomic_add v3, v1, s[4:5] offset:2176
	global_atomic_add v3, v1, s[4:5] offset:2304
	global_atomic_add v3, v1, s[4:5] offset:2432
	global_atomic_add v3, v1, s[4:5] offset:2560
	global_atomic_add v3, v1, s[4:5] offset:2688
	global_atomic_add v3, v1, s[4:5] offset:2816
	global_atomic_add v3, v1, s[4:5] offset:2944
.Lgs4_poll:
	global_load_dword v2, v0, s[4:5] offset:2048 sc1
	s_waitcnt vmcnt(0)
	v_cmp_le_u32_e32 vcc, 4, v2
	s_cbranch_vccnz .Lgs4_done
	s_sleep 1
	s_branch .Lgs4_poll

.LBB0_862:
	s_waitcnt vmcnt(0)
	s_barrier
	s_and_saveexec_b64 s[0:1], s[88:89]
	s_cbranch_execz .LBB0_872
	buffer_wbl2 sc1
	s_load_dwordx2 s[4:5], s[90:91], -0x8
	s_load_dword s6, s[90:91], 0x0
	s_and_b32 s7, s2, 7
	s_lshl_b32 s7, s7, 7
	v_mov_b32_e32 v0, s7
	v_mov_b32_e32 v1, 1
	v_mov_b32_e32 v3, 0
	s_waitcnt vmcnt(0) lgkmcnt(0)
	global_atomic_add v2, v0, v1, s[4:5] offset:1024 sc0
	s_lshr_b32 s6, s6, 3
	s_mul_i32 s6, s6, 5
	s_add_i32 s6, s6, -1
	s_waitcnt vmcnt(0)
	v_cmp_eq_u32_e32 vcc, s6, v2
	s_cbranch_vccz .Lgs5_poll
	global_atomic_add v2, v3, v1, s[4:5] offset:512 sc0
	s_movk_i32 s6, 39
	s_waitcnt vmcnt(0)
	v_cmp_eq_u32_e32 vcc, s6, v2
	s_cbranch_vccz .Lgs5_poll
	global_atomic_add v3, v1, s[4:5] offset:2048
	global_atomic_add v3, v1, s[4:5] offset:2176
	global_atomic_add v3, v1, s[4:5] offset:2304
	global_atomic_add v3, v1, s[4:5] offset:2432
	global_atomic_add v3, v1, s[4:5] offset:2560
	global_atomic_add v3, v1, s[4:5] offset:2688
	global_atomic_add v3, v1, s[4:5] offset:2816
	global_atomic_add v3, v1, s[4:5] offset:2944
.Lgs5_poll:
	global_load_dword v2, v0, s[4:5] offset:2048 sc1
	s_waitcnt vmcnt(0)
	v_cmp_le_u32_e32 vcc, 5, v2
	s_cbranch_vccnz .Lgs5_done
	s_sleep 1
	s_branch .Lgs5_poll

.LBB0_920:
	s_waitcnt vmcnt(0)
	s_barrier
	s_and_saveexec_b64 s[0:1], s[88:89]
	s_cbranch_execz .LBB0_930
	buffer_wbl2 sc1
	s_load_dwordx2 s[4:5], s[90:91], -0x8
	s_load_dword s6, s[90:91], 0x0
	s_and_b32 s7, s2, 7
	s_lshl_b32 s7, s7, 7
	v_mov_b32_e32 v0, s7
	v_mov_b32_e32 v1, 1
	v_mov_b32_e32 v3, 0
	s_waitcnt vmcnt(0) lgkmcnt(0)
	global_atomic_add v2, v0, v1, s[4:5] offset:1024 sc0
	s_lshr_b32 s6, s6, 3
	s_mul_i32 s6, s6, 6
	s_add_i32 s6, s6, -1
	s_waitcnt vmcnt(0)
	v_cmp_eq_u32_e32 vcc, s6, v2
	s_cbranch_vccz .Lgs6_poll
	global_atomic_add v2, v3, v1, s[4:5] offset:512 sc0
	s_movk_i32 s6, 47
	s_waitcnt vmcnt(0)
	v_cmp_eq_u32_e32 vcc, s6, v2
	s_cbranch_vccz .Lgs6_poll
	global_atomic_add v3, v1, s[4:5] offset:2048
	global_atomic_add v3, v1, s[4:5] offset:2176
	global_atomic_add v3, v1, s[4:5] offset:2304
	global_atomic_add v3, v1, s[4:5] offset:2432
	global_atomic_add v3, v1, s[4:5] offset:2560
	global_atomic_add v3, v1, s[4:5] offset:2688
	global_atomic_add v3, v1, s[4:5] offset:2816
	global_atomic_add v3, v1, s[4:5] offset:2944
.Lgs6_poll:
	global_load_dword v2, v0, s[4:5] offset:2048 sc1
	s_waitcnt vmcnt(0)
	v_cmp_le_u32_e32 vcc, 6, v2
	s_cbranch_vccnz .Lgs6_done
	s_sleep 1
	s_branch .Lgs6_poll

.LBB0_933:
	s_or_b64 exec, exec, s[0:1]
	s_waitcnt vmcnt(0)
	s_barrier
	s_and_saveexec_b64 s[0:1], s[88:89]
	s_cbranch_execz .LBB0_943
	buffer_wbl2 sc1
	s_load_dwordx2 s[4:5], s[90:91], -0x8
	s_load_dword s6, s[90:91], 0x0
	s_and_b32 s7, s2, 7
	s_lshl_b32 s7, s7, 7
	v_mov_b32_e32 v0, s7
	v_mov_b32_e32 v1, 1
	v_mov_b32_e32 v3, 0
	s_waitcnt vmcnt(0) lgkmcnt(0)
	global_atomic_add v2, v0, v1, s[4:5] offset:1024 sc0
	s_lshr_b32 s6, s6, 3
	s_mul_i32 s6, s6, 7
	s_add_i32 s6, s6, -1
	s_waitcnt vmcnt(0)
	v_cmp_eq_u32_e32 vcc, s6, v2
	s_cbranch_vccz .Lgs7_poll
	global_atomic_add v2, v3, v1, s[4:5] offset:512 sc0
	s_movk_i32 s6, 55
	s_waitcnt vmcnt(0)
	v_cmp_eq_u32_e32 vcc, s6, v2
	s_cbranch_vccz .Lgs7_poll
	global_atomic_add v3, v1, s[4:5] offset:2048
	global_atomic_add v3, v1, s[4:5] offset:2176
	global_atomic_add v3, v1, s[4:5] offset:2304
	global_atomic_add v3, v1, s[4:5] offset:2432
	global_atomic_add v3, v1, s[4:5] offset:2560
	global_atomic_add v3, v1, s[4:5] offset:2688
	global_atomic_add v3, v1, s[4:5] offset:2816
	global_atomic_add v3, v1, s[4:5] offset:2944
.Lgs7_poll:
	global_load_dword v2, v0, s[4:5] offset:2048 sc1
	s_waitcnt vmcnt(0)
	v_cmp_le_u32_e32 vcc, 7, v2
	s_cbranch_vccnz .Lgs7_done
	s_sleep 1
	s_branch .Lgs7_poll

.LBB0_1017:
	s_waitcnt vmcnt(0)
	s_barrier
	s_and_saveexec_b64 s[0:1], s[88:89]
	s_cbranch_execz .LBB0_1027
	buffer_wbl2 sc1
	s_load_dwordx2 s[4:5], s[90:91], -0x8
	s_load_dword s6, s[90:91], 0x0
	s_and_b32 s7, s2, 7
	s_lshl_b32 s7, s7, 7
	v_mov_b32_e32 v0, s7
	v_mov_b32_e32 v1, 1
	v_mov_b32_e32 v3, 0
	s_waitcnt vmcnt(0) lgkmcnt(0)
	global_atomic_add v2, v0, v1, s[4:5] offset:1024 sc0
	s_lshr_b32 s6, s6, 3
	s_mul_i32 s6, s6, 8
	s_add_i32 s6, s6, -1
	s_waitcnt vmcnt(0)
	v_cmp_eq_u32_e32 vcc, s6, v2
	s_cbranch_vccz .Lgs8_poll
	global_atomic_add v2, v3, v1, s[4:5] offset:512 sc0
	s_movk_i32 s6, 63
	s_waitcnt vmcnt(0)
	v_cmp_eq_u32_e32 vcc, s6, v2
	s_cbranch_vccz .Lgs8_poll
	global_atomic_add v3, v1, s[4:5] offset:2048
	global_atomic_add v3, v1, s[4:5] offset:2176
	global_atomic_add v3, v1, s[4:5] offset:2304
	global_atomic_add v3, v1, s[4:5] offset:2432
	global_atomic_add v3, v1, s[4:5] offset:2560
	global_atomic_add v3, v1, s[4:5] offset:2688
	global_atomic_add v3, v1, s[4:5] offset:2816
	global_atomic_add v3, v1, s[4:5] offset:2944
.Lgs8_poll:
	global_load_dword v2, v0, s[4:5] offset:2048 sc1
	s_waitcnt vmcnt(0)
	v_cmp_le_u32_e32 vcc, 8, v2
	s_cbranch_vccnz .Lgs8_done
	s_sleep 1
	s_branch .Lgs8_poll

.LBB0_1035:
	s_waitcnt vmcnt(0)
	s_barrier
	s_and_saveexec_b64 s[0:1], s[88:89]
	s_cbranch_execz .LBB0_1045
	buffer_wbl2 sc1
	s_load_dwordx2 s[4:5], s[90:91], -0x8
	s_load_dword s6, s[90:91], 0x0
	s_and_b32 s7, s2, 7
	s_lshl_b32 s7, s7, 7
	v_mov_b32_e32 v0, s7
	v_mov_b32_e32 v1, 1
	v_mov_b32_e32 v3, 0
	s_waitcnt vmcnt(0) lgkmcnt(0)
	global_atomic_add v2, v0, v1, s[4:5] offset:1024 sc0
	s_lshr_b32 s6, s6, 3
	s_mul_i32 s6, s6, 9
	s_add_i32 s6, s6, -1
	s_waitcnt vmcnt(0)
	v_cmp_eq_u32_e32 vcc, s6, v2
	s_cbranch_vccz .Lgs9_poll
	global_atomic_add v2, v3, v1, s[4:5] offset:512 sc0
	s_movk_i32 s6, 71
	s_waitcnt vmcnt(0)
	v_cmp_eq_u32_e32 vcc, s6, v2
	s_cbranch_vccz .Lgs9_poll
	global_atomic_add v3, v1, s[4:5] offset:2048
	global_atomic_add v3, v1, s[4:5] offset:2176
	global_atomic_add v3, v1, s[4:5] offset:2304
	global_atomic_add v3, v1, s[4:5] offset:2432
	global_atomic_add v3, v1, s[4:5] offset:2560
	global_atomic_add v3, v1, s[4:5] offset:2688
	global_atomic_add v3, v1, s[4:5] offset:2816
	global_atomic_add v3, v1, s[4:5] offset:2944
.Lgs9_poll:
	global_load_dword v2, v0, s[4:5] offset:2048 sc1
	s_waitcnt vmcnt(0)
	v_cmp_le_u32_e32 vcc, 9, v2
	s_cbranch_vccnz .Lgs9_done
	s_sleep 1
	s_branch .Lgs9_poll

.LBB0_1057:
	s_or_b64 exec, exec, s[0:1]
	s_waitcnt vmcnt(0)
	s_barrier
	s_and_saveexec_b64 s[0:1], s[88:89]
	s_cbranch_execz .LBB0_1067
	buffer_wbl2 sc1
	s_load_dwordx2 s[4:5], s[90:91], -0x8
	s_load_dword s6, s[90:91], 0x0
	s_and_b32 s7, s2, 7
	s_lshl_b32 s7, s7, 7
	v_mov_b32_e32 v0, s7
	v_mov_b32_e32 v1, 1
	v_mov_b32_e32 v3, 0
	s_waitcnt vmcnt(0) lgkmcnt(0)
	global_atomic_add v2, v0, v1, s[4:5] offset:1024 sc0
	s_lshr_b32 s6, s6, 3
	s_mul_i32 s6, s6, 10
	s_add_i32 s6, s6, -1
	s_waitcnt vmcnt(0)
	v_cmp_eq_u32_e32 vcc, s6, v2
	s_cbranch_vccz .Lgs10_poll
	global_atomic_add v2, v3, v1, s[4:5] offset:512 sc0
	s_movk_i32 s6, 79
	s_waitcnt vmcnt(0)
	v_cmp_eq_u32_e32 vcc, s6, v2
	s_cbranch_vccz .Lgs10_poll
	global_atomic_add v3, v1, s[4:5] offset:2048
	global_atomic_add v3, v1, s[4:5] offset:2176
	global_atomic_add v3, v1, s[4:5] offset:2304
	global_atomic_add v3, v1, s[4:5] offset:2432
	global_atomic_add v3, v1, s[4:5] offset:2560
	global_atomic_add v3, v1, s[4:5] offset:2688
	global_atomic_add v3, v1, s[4:5] offset:2816
	global_atomic_add v3, v1, s[4:5] offset:2944
.Lgs10_poll:
	global_load_dword v2, v0, s[4:5] offset:2048 sc1
	s_waitcnt vmcnt(0)
	v_cmp_le_u32_e32 vcc, 10, v2
	s_cbranch_vccnz .Lgs10_done
	s_sleep 1
	s_branch .Lgs10_poll

.LBB0_1075:
	s_waitcnt vmcnt(0)
	s_barrier
	s_and_saveexec_b64 s[0:1], s[88:89]
	s_cbranch_execz .LBB0_1085
	buffer_wbl2 sc1
	s_load_dwordx2 s[4:5], s[90:91], -0x8
	s_load_dword s6, s[90:91], 0x0
	s_and_b32 s7, s2, 7
	s_lshl_b32 s7, s7, 7
	v_mov_b32_e32 v0, s7
	v_mov_b32_e32 v1, 1
	v_mov_b32_e32 v3, 0
	s_waitcnt vmcnt(0) lgkmcnt(0)
	global_atomic_add v2, v0, v1, s[4:5] offset:1024 sc0
	s_lshr_b32 s6, s6, 3
	s_mul_i32 s6, s6, 11
	s_add_i32 s6, s6, -1
	s_waitcnt vmcnt(0)
	v_cmp_eq_u32_e32 vcc, s6, v2
	s_cbranch_vccz .Lgs11_poll
	global_atomic_add v2, v3, v1, s[4:5] offset:512 sc0
	s_movk_i32 s6, 87
	s_waitcnt vmcnt(0)
	v_cmp_eq_u32_e32 vcc, s6, v2
	s_cbranch_vccz .Lgs11_poll
	global_atomic_add v3, v1, s[4:5] offset:2048
	global_atomic_add v3, v1, s[4:5] offset:2176
	global_atomic_add v3, v1, s[4:5] offset:2304
	global_atomic_add v3, v1, s[4:5] offset:2432
	global_atomic_add v3, v1, s[4:5] offset:2560
	global_atomic_add v3, v1, s[4:5] offset:2688
	global_atomic_add v3, v1, s[4:5] offset:2816
	global_atomic_add v3, v1, s[4:5] offset:2944
.Lgs11_poll:
	global_load_dword v2, v0, s[4:5] offset:2048 sc1
	s_waitcnt vmcnt(0)
	v_cmp_le_u32_e32 vcc, 11, v2
	s_cbranch_vccnz .Lgs11_done
	s_sleep 1
	s_branch .Lgs11_poll

.LBB0_1229:
	s_waitcnt vmcnt(63) expcnt(7) lgkmcnt(15)
	s_waitcnt vmcnt(0)
	s_barrier
	s_and_saveexec_b64 s[0:1], s[88:89]
	s_cbranch_execz .LBB0_1239
	buffer_wbl2 sc1
	s_load_dwordx2 s[4:5], s[90:91], -0x8
	s_load_dword s8, s[90:91], 0x0
	s_and_b32 s9, s2, 7
	s_lshl_b32 s9, s9, 7
	v_mov_b32_e32 v0, s9
	v_mov_b32_e32 v1, 1
	v_mov_b32_e32 v3, 0
	s_waitcnt vmcnt(0) lgkmcnt(0)
	global_atomic_add v2, v0, v1, s[4:5] offset:1024 sc0
	s_lshr_b32 s8, s8, 3
	s_mul_i32 s8, s8, 12
	s_add_i32 s8, s8, -1
	s_waitcnt vmcnt(0)
	v_cmp_eq_u32_e32 vcc, s8, v2
	s_cbranch_vccz .Lgs12_poll
	global_atomic_add v2, v3, v1, s[4:5] offset:512 sc0
	s_movk_i32 s8, 95
	s_waitcnt vmcnt(0)
	v_cmp_eq_u32_e32 vcc, s8, v2
	s_cbranch_vccz .Lgs12_poll
	global_atomic_add v3, v1, s[4:5] offset:2048
	global_atomic_add v3, v1, s[4:5] offset:2176
	global_atomic_add v3, v1, s[4:5] offset:2304
	global_atomic_add v3, v1, s[4:5] offset:2432
	global_atomic_add v3, v1, s[4:5] offset:2560
	global_atomic_add v3, v1, s[4:5] offset:2688
	global_atomic_add v3, v1, s[4:5] offset:2816
	global_atomic_add v3, v1, s[4:5] offset:2944
.Lgs12_poll:
	global_load_dword v2, v0, s[4:5] offset:2048 sc1
	s_waitcnt vmcnt(0)
	v_cmp_le_u32_e32 vcc, 12, v2
	s_cbranch_vccnz .Lgs12_done
	s_sleep 1
	s_branch .Lgs12_poll
